# GEMM1 k-loop: LDS-DMA m0 stepping with one readfirstlane plus scalar adds (11 fewer VALU-class ops per k-step), on top of two-level fragment wait
# speedup vs baseline: 1.0491x; 1.0003x over previous
; template <int MODE>
; __device__ void phase_gemm(const Params& p, int l, char* smem, int mtiles, int* s_item, int wv) {
;     ...
;     auto stage = [&](int kt, int buf) {
;       char* SA = smem + buf * 24576;
;       char* SB = SA + 16384;
;       const char* ab = (const char*)A + ((size_t)brow * 1024 + kt * 32) * 2;
;       const char* bb = (const char*)Bt + ((size_t)bcol * 1024 + kt * 32) * 2;
; #pragma unroll
;       for (int i = 0; i < 4; ++i) glds16(ab + (size_t)i * (64 * 2048) + voff, SA + tid * 16 + i * 4096);
; #pragma unroll
;       for (int i = 0; i < 2; ++i) glds16(bb + (size_t)i * (64 * 2048) + voff, SB + tid * 16 + i * 4096);
;     };
;     __syncthreads();
;     stage(0, 0);
;     stage(1, 1);
;     int buf = 0;
;     for (int kt = 0; kt < 32; ++kt) {
;       if (kt < 31) asm volatile("s_waitcnt vmcnt(6)" ::: "memory");
;       else asm volatile("s_waitcnt vmcnt(0)" ::: "memory");
;       __builtin_amdgcn_s_barrier();
;       int nb = buf + 2; nb = nb >= 3 ? nb - 3 : nb;
;       if (kt + 2 < 32) stage(kt + 2, nb);
;       const char* SA = smem + buf * 24576;
;       const char* SB = SA + 16384;
;       bf16x8 af[8], bfr[4];
; #pragma unroll
;       for (int n = 0; n < 4; ++n) bfr[n] = *(const bf16x8*)(SB + (wc * 64 + n * 16 + fr) * 64 + (fq ^ (fr >> 2)) * 16);
; #pragma unroll
;       for (int m = 0; m < 8; ++m) af[m] = *(const bf16x8*)(SA + (wr * 128 + m * 16 + fr) * 64 + (fq ^ (fr >> 2)) * 16);
;       __builtin_amdgcn_sched_barrier(0);
;       __builtin_amdgcn_s_setprio(1);
; #pragma unroll
;       for (int m = 0; m < 8; ++m)
; #pragma unroll
;         for (int n = 0; n < 4; ++n) acc[m][n] = mfma16(bfr[n], af[m], acc[m][n]);
;       __builtin_amdgcn_s_setprio(0);
;       buf = buf + 1 == 3 ? 0 : buf + 1;
;     }
.LBB0_180:
	s_cmp_gt_i32 s1, 0
	s_cselect_b32 s39, -1, 2
	s_add_i32 s39, s39, s1
	s_mulk_i32 s39, 0x6000
	v_readfirstlane_b32 s40, v147
	v_lshl_add_u64 v[142:143], v[140:141], 0, s[2:3]
	s_add_u32 s39, s39, s40
	v_lshl_add_u64 v[144:145], v[142:143], 0, s[52:53]
	s_mov_b32 m0, s39
	s_waitcnt vmcnt(6)
	s_barrier
	global_load_lds_dwordx4 v[144:145], off
	s_add_u32 m0, s39, 0x1000
	v_lshl_add_u64 v[144:145], v[142:143], 0, s[54:55]
	global_load_lds_dwordx4 v[144:145], off
	s_add_u32 m0, s39, 0x2000
	v_lshl_add_u64 v[144:145], v[142:143], 0, s[56:57]
	global_load_lds_dwordx4 v[144:145], off
	s_add_u32 m0, s39, 0x3000
	v_lshl_add_u64 v[142:143], v[142:143], 0, s[58:59]
	global_load_lds_dwordx4 v[142:143], off
	s_add_u32 m0, s39, 0x4000
	v_lshl_add_u64 v[142:143], v[138:139], 0, s[2:3]
	s_mov_b64 s[40:41], 0x80
	v_lshl_add_u64 v[144:145], v[142:143], 0, s[40:41]
	global_load_lds_dwordx4 v[144:145], off
	s_add_u32 m0, s39, 0x5000
	s_mov_b64 s[40:41], 0x20080
	v_lshl_add_u64 v[142:143], v[142:143], 0, s[40:41]
	global_load_lds_dwordx4 v[142:143], off
	s_mul_i32 s39, s1, 0x6000
	v_add_u32_e32 v0, s39, v151
	v_add_u32_e32 v160, v0, v148
	v_add_u32_e32 v176, v0, v149
	ds_read_b128 v[142:145], v160 offset:16384
	ds_read_b128 v[152:155], v160 offset:17408
	ds_read_b128 v[156:159], v160 offset:18432
	ds_read_b128 v[160:163], v160 offset:19456
	ds_read_b128 v[164:167], v176
	ds_read_b128 v[168:171], v176 offset:1024
	ds_read_b128 v[172:175], v176 offset:2048
	ds_read_b128 v[182:185], v176 offset:3072
	ds_read_b128 v[186:189], v176 offset:4096
	ds_read_b128 v[190:193], v176 offset:5120
	v_add_u32_e32 v0, v0, v150
	ds_read_b128 v[194:197], v176 offset:6144
	ds_read_b128 v[198:201], v0
	s_setprio 1
	s_waitcnt lgkmcnt(4)
	v_mfma_f32_16x16x32_bf16 v[126:129], v[142:145], v[164:167], v[126:129]
	v_mfma_f32_16x16x32_bf16 v[122:125], v[152:155], v[164:167], v[122:125]
	v_mfma_f32_16x16x32_bf16 v[118:121], v[156:159], v[164:167], v[118:121]
	v_mfma_f32_16x16x32_bf16 v[114:117], v[160:163], v[164:167], v[114:117]
	v_mfma_f32_16x16x32_bf16 v[110:113], v[142:145], v[168:171], v[110:113]
	v_mfma_f32_16x16x32_bf16 v[106:109], v[152:155], v[168:171], v[106:109]
	v_mfma_f32_16x16x32_bf16 v[102:105], v[156:159], v[168:171], v[102:105]
	v_mfma_f32_16x16x32_bf16 v[98:101], v[160:163], v[168:171], v[98:101]
	v_mfma_f32_16x16x32_bf16 v[94:97], v[142:145], v[172:175], v[94:97]
	v_mfma_f32_16x16x32_bf16 v[90:93], v[152:155], v[172:175], v[90:93]
	v_mfma_f32_16x16x32_bf16 v[86:89], v[156:159], v[172:175], v[86:89]
	v_mfma_f32_16x16x32_bf16 v[82:85], v[160:163], v[172:175], v[82:85]
	v_mfma_f32_16x16x32_bf16 v[78:81], v[142:145], v[182:185], v[78:81]
	v_mfma_f32_16x16x32_bf16 v[74:77], v[152:155], v[182:185], v[74:77]
	v_mfma_f32_16x16x32_bf16 v[70:73], v[156:159], v[182:185], v[70:73]
	v_mfma_f32_16x16x32_bf16 v[66:69], v[160:163], v[182:185], v[66:69]
	s_waitcnt lgkmcnt(0)
	v_mfma_f32_16x16x32_bf16 v[62:65], v[142:145], v[186:189], v[62:65]
	v_mfma_f32_16x16x32_bf16 v[58:61], v[152:155], v[186:189], v[58:61]
	v_mfma_f32_16x16x32_bf16 v[54:57], v[156:159], v[186:189], v[54:57]
	v_mfma_f32_16x16x32_bf16 v[50:53], v[160:163], v[186:189], v[50:53]
	v_mfma_f32_16x16x32_bf16 v[46:49], v[142:145], v[190:193], v[46:49]
	v_mfma_f32_16x16x32_bf16 v[42:45], v[152:155], v[190:193], v[42:45]
	v_mfma_f32_16x16x32_bf16 v[38:41], v[156:159], v[190:193], v[38:41]
	v_mfma_f32_16x16x32_bf16 v[34:37], v[160:163], v[190:193], v[34:37]
	v_mfma_f32_16x16x32_bf16 v[30:33], v[142:145], v[194:197], v[30:33]
	v_mfma_f32_16x16x32_bf16 v[26:29], v[152:155], v[194:197], v[26:29]
	v_mfma_f32_16x16x32_bf16 v[22:25], v[156:159], v[194:197], v[22:25]
	v_mfma_f32_16x16x32_bf16 v[18:21], v[160:163], v[194:197], v[18:21]
	v_mfma_f32_16x16x32_bf16 v[14:17], v[142:145], v[198:201], v[14:17]
	v_mfma_f32_16x16x32_bf16 v[10:13], v[152:155], v[198:201], v[10:13]
	v_mfma_f32_16x16x32_bf16 v[6:9], v[156:159], v[198:201], v[6:9]
	v_mfma_f32_16x16x32_bf16 v[2:5], v[160:163], v[198:201], v[2:5]
	s_setprio 0
	s_add_i32 s1, s1, 1
	s_cmp_lg_u32 s1, 3
	s_cselect_b32 s1, s1, 0
	s_add_u32 s2, s2, 64
	s_addc_u32 s3, s3, 0
	s_cmpk_eq_i32 s2, 0x780
	s_cbranch_scc0 .LBB0_180
	s_mulk_i32 s1, 0x6000
	v_add_u32_e32 v0, s1, v151
	v_add_u32_e32 v156, v0, v148
	v_add_u32_e32 v176, v0, v149
	s_waitcnt vmcnt(6)
	s_barrier
; template <int MODE>
; __device__ void phase_gemm(const Params& p, int l, char* smem, int mtiles, int* s_item, int wv) {
;     ...
;     for (int kt = 0; kt < 32; ++kt) {
;       if (kt < 31) asm volatile("s_waitcnt vmcnt(6)" ::: "memory");
;       else asm volatile("s_waitcnt vmcnt(0)" ::: "memory");
;       __builtin_amdgcn_s_barrier();
;       int nb = buf + 2; nb = nb >= 3 ? nb - 3 : nb;
;       if (kt + 2 < 32) stage(kt + 2, nb);
;       const char* SA = smem + buf * 24576;
;       const char* SB = SA + 16384;
;       bf16x8 af[8], bfr[4];
; #pragma unroll
;       for (int n = 0; n < 4; ++n) bfr[n] = *(const bf16x8*)(SB + (wc * 64 + n * 16 + fr) * 64 + (fq ^ (fr >> 2)) * 16);
; #pragma unroll
;       for (int m = 0; m < 8; ++m) af[m] = *(const bf16x8*)(SA + (wr * 128 + m * 16 + fr) * 64 + (fq ^ (fr >> 2)) * 16);
;       __builtin_amdgcn_sched_barrier(0);
;       __builtin_amdgcn_s_setprio(1);
; #pragma unroll
;       for (int m = 0; m < 8; ++m)
; #pragma unroll
;         for (int n = 0; n < 4; ++n) acc[m][n] = mfma16(bfr[n], af[m], acc[m][n]);
;       __builtin_amdgcn_s_setprio(0);
;       buf = buf + 1 == 3 ? 0 : buf + 1;
;     }
	ds_read_b128 v[138:141], v156 offset:16384
	ds_read_b128 v[142:145], v156 offset:17408
	ds_read_b128 v[152:155], v156 offset:18432
	ds_read_b128 v[156:159], v156 offset:19456
	ds_read_b128 v[160:163], v176
	ds_read_b128 v[164:167], v176 offset:1024
	ds_read_b128 v[168:171], v176 offset:2048
	ds_read_b128 v[172:175], v176 offset:3072
	ds_read_b128 v[182:185], v176 offset:4096
	ds_read_b128 v[186:189], v176 offset:5120
	v_add_u32_e32 v0, v0, v150
	ds_read_b128 v[190:193], v176 offset:6144
	ds_read_b128 v[194:197], v0
	s_setprio 1
	s_waitcnt lgkmcnt(0)
	v_mfma_f32_16x16x32_bf16 v[126:129], v[138:141], v[160:163], v[126:129]
	v_mfma_f32_16x16x32_bf16 v[122:125], v[142:145], v[160:163], v[122:125]
	v_mfma_f32_16x16x32_bf16 v[110:113], v[138:141], v[164:167], v[110:113]
	v_mfma_f32_16x16x32_bf16 v[106:109], v[142:145], v[164:167], v[106:109]
	v_mfma_f32_16x16x32_bf16 v[94:97], v[138:141], v[168:171], v[94:97]
	v_mfma_f32_16x16x32_bf16 v[90:93], v[142:145], v[168:171], v[90:93]
	v_mfma_f32_16x16x32_bf16 v[78:81], v[138:141], v[172:175], v[78:81]
	v_mfma_f32_16x16x32_bf16 v[74:77], v[142:145], v[172:175], v[74:77]
	v_mfma_f32_16x16x32_bf16 v[62:65], v[138:141], v[182:185], v[62:65]
	v_mfma_f32_16x16x32_bf16 v[58:61], v[142:145], v[182:185], v[58:61]
	v_mfma_f32_16x16x32_bf16 v[46:49], v[138:141], v[186:189], v[46:49]
	v_mfma_f32_16x16x32_bf16 v[42:45], v[142:145], v[186:189], v[42:45]
	v_mfma_f32_16x16x32_bf16 v[30:33], v[138:141], v[190:193], v[30:33]
	v_mfma_f32_16x16x32_bf16 v[26:29], v[142:145], v[190:193], v[26:29]
	v_mfma_f32_16x16x32_bf16 v[14:17], v[138:141], v[194:197], v[14:17]
	v_mfma_f32_16x16x32_bf16 v[10:13], v[142:145], v[194:197], v[10:13]
	v_mfma_f32_16x16x32_bf16 v[138:141], v[152:155], v[194:197], v[6:9]
	v_mfma_f32_16x16x32_bf16 v[142:145], v[156:159], v[194:197], v[2:5]
	v_mfma_f32_16x16x32_bf16 v[198:201], v[152:155], v[160:163], v[118:121]
	v_mfma_f32_16x16x32_bf16 v[160:163], v[156:159], v[160:163], v[114:117]
	v_mfma_f32_16x16x32_bf16 v[202:205], v[152:155], v[164:167], v[102:105]
	v_mfma_f32_16x16x32_bf16 v[164:167], v[156:159], v[164:167], v[98:101]
	v_mfma_f32_16x16x32_bf16 v[206:209], v[152:155], v[168:171], v[86:89]
	v_mfma_f32_16x16x32_bf16 v[168:171], v[156:159], v[168:171], v[82:85]
	v_mfma_f32_16x16x32_bf16 v[210:213], v[152:155], v[172:175], v[70:73]
	v_mfma_f32_16x16x32_bf16 v[172:175], v[156:159], v[172:175], v[66:69]
	v_mfma_f32_16x16x32_bf16 v[214:217], v[152:155], v[182:185], v[54:57]
	v_mfma_f32_16x16x32_bf16 v[182:185], v[156:159], v[182:185], v[50:53]
	v_mfma_f32_16x16x32_bf16 v[218:221], v[152:155], v[186:189], v[38:41]
	v_mfma_f32_16x16x32_bf16 v[186:189], v[156:159], v[186:189], v[34:37]
	v_mfma_f32_16x16x32_bf16 v[222:225], v[152:155], v[190:193], v[22:25]
	v_mfma_f32_16x16x32_bf16 v[190:193], v[156:159], v[190:193], v[18:21]
	s_setprio 0
	v_add_u32_e32 v0, v151, v148
	s_waitcnt vmcnt(0)
	s_barrier
; template <int MODE>
; __device__ void phase_gemm(const Params& p, int l, char* smem, int mtiles, int* s_item, int wv) {
;     ...
;       const char* SA = smem + buf * 24576;
;       const char* SB = SA + 16384;
;       bf16x8 af[8], bfr[4];
; #pragma unroll
;       for (int n = 0; n < 4; ++n) bfr[n] = *(const bf16x8*)(SB + (wc * 64 + n * 16 + fr) * 64 + (fq ^ (fr >> 2)) * 16);
; #pragma unroll
;       for (int m = 0; m < 8; ++m) af[m] = *(const bf16x8*)(SA + (wr * 128 + m * 16 + fr) * 64 + (fq ^ (fr >> 2)) * 16);
;       __builtin_amdgcn_sched_barrier(0);
;       __builtin_amdgcn_s_setprio(1);
; #pragma unroll
;       for (int m = 0; m < 8; ++m)
; #pragma unroll
;         for (int n = 0; n < 4; ++n) acc[m][n] = mfma16(bfr[n], af[m], acc[m][n]);
;       __builtin_amdgcn_s_setprio(0);
;       buf = buf + 1 == 3 ? 0 : buf + 1;
;     }
;     int tid_e = tid;
;     asm volatile("" : "+v"(tid_e));
;     const int fr = tid_e & 15, fq = (tid_e >> 4) & 3, wr = tid_e >> 7, wc = (tid_e >> 6) & 1;
;     const int col0 = bcol + wc * 64;
;     if (MODE == 1) {
;       u16* P = (u16*)(p.ws + OFF_P);
;       float* SC = (float*)(p.ws + OFF_SC);
;       const float2* rope = (const float2*)(p.ws + OFF_ROPE);
;       if (col0 >= 3328) {
;         if (col0 == 3328) {
; #pragma unroll
;           for (int m = 0; m < 8; ++m) {
;             int row = brow + wr * 128 + m * 16 + fr;
; #pragma unroll
;             for (int n = 0; n < 2; ++n)
;               *(float4*)(SC + (size_t)row * 32 + n * 16 + fq * 4) =
;                   make_float4(acc[m][n][0], acc[m][n][1], acc[m][n][2], acc[m][n][3]);
;           }
;         }
;       } else {
;         const bool ropecols = col0 >= C_QC && col0 < C_VC;
;         const bool isq = col0 >= C_QC && col0 < C_KC;
; #pragma unroll
;         for (int m = 0; m < 8; ++m) {
;           int row = brow + wr * 128 + m * 16 + fr;
;           if (ropecols && row < NL) {
;             int tpos = row & 4095;
; #pragma unroll
;             for (int pr = 0; pr < 2; ++pr) {
;               int pos = pr == 0 ? (tpos >> 6) : (tpos & 63);
; #pragma unroll
;               for (int j = 0; j < 4; ++j) {
;                 float2 cs = rope[pos * 16 + fq * 4 + j];
;                 float x1 = acc[m][2 * pr][j], x2 = acc[m][2 * pr + 1][j];
;                 acc[m][2 * pr][j] = x1 * cs.x - x2 * cs.y;
;                 acc[m][2 * pr + 1][j] = x2 * cs.x + x1 * cs.y;
	ds_read_b128 v[2:5], v0 offset:40960
	ds_read_b128 v[152:155], v0 offset:41984
	ds_read_b128 v[156:159], v0 offset:43008
	ds_read_b128 v[194:197], v0 offset:44032
	v_add_u32_e32 v0, v151, v149
	ds_read_b128 v[6:9], v0 offset:24576
	ds_read_b128 v[18:21], v0 offset:25600
	ds_read_b128 v[22:25], v0 offset:26624
	ds_read_b128 v[34:37], v0 offset:27648
	ds_read_b128 v[38:41], v0 offset:28672
	ds_read_b128 v[226:229], v0 offset:29696
	v_add_u32_e32 v50, v151, v150
	ds_read_b128 v[230:233], v0 offset:30720
	ds_read_b128 v[234:237], v50 offset:24576
	s_setprio 1
	s_waitcnt lgkmcnt(4)
	v_mfma_f32_16x16x32_bf16 v[118:121], v[2:5], v[6:9], v[126:129]
	v_mfma_f32_16x16x32_bf16 v[114:117], v[152:155], v[6:9], v[122:125]
	v_mfma_f32_16x16x32_bf16 v[126:129], v[156:159], v[6:9], v[198:201]
	v_mfma_f32_16x16x32_bf16 v[122:125], v[194:197], v[6:9], v[160:163]
	v_mfma_f32_16x16x32_bf16 v[102:105], v[2:5], v[18:21], v[110:113]
	v_mfma_f32_16x16x32_bf16 v[98:101], v[152:155], v[18:21], v[106:109]
	v_mfma_f32_16x16x32_bf16 v[110:113], v[156:159], v[18:21], v[202:205]
	v_mfma_f32_16x16x32_bf16 v[106:109], v[194:197], v[18:21], v[164:167]
	v_mfma_f32_16x16x32_bf16 v[86:89], v[2:5], v[22:25], v[94:97]
	v_mfma_f32_16x16x32_bf16 v[82:85], v[152:155], v[22:25], v[90:93]
	v_mfma_f32_16x16x32_bf16 v[94:97], v[156:159], v[22:25], v[206:209]
	v_mfma_f32_16x16x32_bf16 v[90:93], v[194:197], v[22:25], v[168:171]
	v_mfma_f32_16x16x32_bf16 v[70:73], v[2:5], v[34:37], v[78:81]
	v_mfma_f32_16x16x32_bf16 v[66:69], v[152:155], v[34:37], v[74:77]
	v_mfma_f32_16x16x32_bf16 v[78:81], v[156:159], v[34:37], v[210:213]
	v_mfma_f32_16x16x32_bf16 v[74:77], v[194:197], v[34:37], v[172:175]
	s_waitcnt lgkmcnt(0)
	v_mfma_f32_16x16x32_bf16 v[54:57], v[2:5], v[38:41], v[62:65]
	v_mfma_f32_16x16x32_bf16 v[50:53], v[152:155], v[38:41], v[58:61]
	v_mfma_f32_16x16x32_bf16 v[62:65], v[156:159], v[38:41], v[214:217]
	v_mfma_f32_16x16x32_bf16 v[58:61], v[194:197], v[38:41], v[182:185]
	v_mfma_f32_16x16x32_bf16 v[38:41], v[2:5], v[226:229], v[46:49]
	v_mfma_f32_16x16x32_bf16 v[34:37], v[152:155], v[226:229], v[42:45]
	v_mfma_f32_16x16x32_bf16 v[46:49], v[156:159], v[226:229], v[218:221]
	v_mfma_f32_16x16x32_bf16 v[42:45], v[194:197], v[226:229], v[186:189]
	v_mfma_f32_16x16x32_bf16 v[22:25], v[2:5], v[230:233], v[30:33]
	v_mfma_f32_16x16x32_bf16 v[18:21], v[152:155], v[230:233], v[26:29]
	v_mfma_f32_16x16x32_bf16 v[30:33], v[156:159], v[230:233], v[222:225]
	v_mfma_f32_16x16x32_bf16 v[26:29], v[194:197], v[230:233], v[190:193]
	v_mfma_f32_16x16x32_bf16 v[6:9], v[2:5], v[234:237], v[14:17]
	v_mfma_f32_16x16x32_bf16 v[2:5], v[152:155], v[234:237], v[10:13]
	v_mfma_f32_16x16x32_bf16 v[14:17], v[156:159], v[234:237], v[138:141]
	v_mfma_f32_16x16x32_bf16 v[10:13], v[194:197], v[234:237], v[142:145]
	s_setprio 0
	s_nop 0
	v_mov_b32_e32 v139, v146
	s_nop 0
	v_and_or_b32 v142, v139, 64, s0
	v_and_b32_e32 v153, 15, v139
	v_bfe_u32 v138, v139, 4, 2
	v_cmp_gt_i32_e32 vcc, s69, v142
	s_and_saveexec_b64 s[0:1], vcc
	s_xor_b64 s[40:41], exec, s[0:1]
	s_cbranch_execz .LBB0_231
	v_and_b32_e32 v139, 0xffffff80, v139
	v_add_u32_e32 v154, s38, v139
	v_add_u32_e32 v0, 0xfffff700, v142
	s_movk_i32 s0, 0x200
	v_or_b32_e32 v157, v154, v153
	v_cmp_gt_u32_e32 vcc, s0, v0
	v_lshlrev_b32_e32 v152, 2, v138
	v_cmp_gt_i32_e64 s[0:1], s70, v157
	s_and_b64 s[2:3], vcc, s[0:1]
	v_lshrrev_b32_e32 v138, 2, v154
	v_lshlrev_b32_e32 v139, 3, v152
	s_movk_i32 s0, 0x3e0
	v_and_or_b32 v156, v138, s0, v152
	v_lshl_or_b32 v155, v153, 7, v139
	s_and_saveexec_b64 s[0:1], s[2:3]
	s_cbranch_execz .LBB0_184
	v_lshlrev_b32_e32 v143, 3, v156
	global_load_dwordx4 v[138:141], v143, s[34:35] offset:16
	global_load_dwordx4 v[158:161], v143, s[34:35]
	s_waitcnt vmcnt(0)
	v_mul_f32_e32 v164, v116, v139
	v_mul_f32_e32 v166, v116, v138
	v_mov_b32_e32 v116, v121
	v_mov_b32_e32 v145, v160
	v_mov_b32_e32 v160, v159
	v_mul_f32_e32 v162, v120, v138
	v_mul_f32_e32 v168, v120, v139
	v_pk_mul_f32 v[138:139], v[116:117], v[140:141]
	v_mov_b32_e32 v144, v158
	v_pk_mul_f32 v[158:159], v[118:119], v[160:161]
	v_pk_mul_f32 v[160:161], v[114:115], v[160:161]
	v_mov_b32_e32 v163, v138
	v_mov_b32_e32 v165, v139
	v_pk_fma_f32 v[118:119], v[118:119], v[144:145], v[160:161] neg_lo:[0,0,1] neg_hi:[0,0,1]
	v_pk_add_f32 v[138:139], v[162:163], v[164:165] neg_lo:[0,1] neg_hi:[0,1]
	v_pk_fma_f32 v[114:115], v[114:115], v[144:145], v[158:159]
	global_load_dwordx4 v[158:161], v155, s[34:35] offset:16
	global_load_dwordx4 v[162:165], v155, s[34:35]
	v_mov_b32_e32 v120, v117
	v_pk_mul_f32 v[116:117], v[120:121], v[140:141]
	s_waitcnt vmcnt(0)
	v_mov_b32_e32 v121, v164
	v_mov_b32_e32 v164, v163
	v_mov_b32_e32 v167, v116
	v_mov_b32_e32 v169, v117
	v_mov_b32_e32 v120, v162
	v_pk_mul_f32 v[140:141], v[126:127], v[164:165]
	v_pk_mul_f32 v[144:145], v[122:123], v[164:165]
	v_mul_f32_e32 v162, v128, v158
	v_mul_f32_e32 v164, v124, v159
	v_mul_f32_e32 v158, v124, v158
	v_mov_b32_e32 v124, v129
	v_pk_add_f32 v[116:117], v[166:167], v[168:169]
	v_mul_f32_e32 v166, v128, v159
	v_pk_mul_f32 v[168:169], v[124:125], v[160:161]
	v_mov_b32_e32 v128, v125
	v_mov_b32_e32 v163, v168
	v_mov_b32_e32 v165, v169
	v_pk_mul_f32 v[124:125], v[128:129], v[160:161]
	v_pk_fma_f32 v[126:127], v[126:127], v[120:121], v[144:145] neg_lo:[0,0,1] neg_hi:[0,0,1]
	v_pk_add_f32 v[144:145], v[162:163], v[164:165] neg_lo:[0,1] neg_hi:[0,1]
	v_mov_b32_e32 v159, v124
	v_mov_b32_e32 v167, v125
	v_pk_fma_f32 v[122:123], v[122:123], v[120:121], v[140:141]
	v_pk_add_f32 v[124:125], v[158:159], v[166:167]
	v_mov_b32_e32 v128, v144
	v_mov_b32_e32 v129, v145
	v_mov_b32_e32 v120, v138
	v_mov_b32_e32 v121, v139
